# P5/P6 full-tile K loops: the eight never-taken quarter-mode branches between MFMA groups removed (quarter units run their own loop)
# speedup vs baseline: 1.0056x; 1.0022x over previous
.LBB0_1132:
	s_andn2_b64 vcc, exec, s[26:27]
	s_cbranch_vccnz .Lq5_entry
	ds_read_b128 v[148:151], v214
	ds_read_b128 v[152:155], v214 offset:1024
	ds_read_b128 v[156:159], v214 offset:2048
	ds_read_b128 v[160:163], v214 offset:3072
	ds_read_b128 v[132:135], v215
	ds_read_b128 v[136:139], v215 offset:1024
	ds_read_b128 v[140:143], v215 offset:2048
	ds_read_b128 v[144:147], v215 offset:3072
	v_lshl_add_u64 v[2:3], s[34:35], 0, v[200:201]
	s_add_i32 m0, s48, 0xc000
	s_waitcnt lgkmcnt(0)
	ds_read_b128 v[188:191], v216
	ds_read_b128 v[192:195], v216 offset:1024
	ds_read_b128 v[180:183], v216 offset:2048
	ds_read_b128 v[184:187], v216 offset:3072
	ds_read_b128 v[172:175], v216 offset:4096
	ds_read_b128 v[176:179], v216 offset:5120
	ds_read_b128 v[164:167], v216 offset:6144
	ds_read_b128 v[168:171], v216 offset:7168
	global_load_lds_dwordx4 v[2:3], off
	v_lshl_add_u64 v[2:3], s[34:35], 0, v[202:203]
	s_add_i32 m0, s48, 0xe000
	s_nop 0
	global_load_lds_dwordx4 v[2:3], off
	s_waitcnt vmcnt(8)
	s_waitcnt lgkmcnt(0)
	s_barrier
	s_setprio 1
	s_waitcnt lgkmcnt(0)
	v_mfma_f32_16x16x32_bf16 v[128:131], v[148:151], v[188:191], v[128:131]
	v_mfma_f32_16x16x32_bf16 v[124:127], v[156:159], v[188:191], v[124:127]
	v_mfma_f32_16x16x32_bf16 v[120:123], v[148:151], v[180:183], v[120:123]
	v_mfma_f32_16x16x32_bf16 v[116:119], v[156:159], v[180:183], v[116:119]
	v_mfma_f32_16x16x32_bf16 v[104:107], v[148:151], v[172:175], v[104:107]
	v_mfma_f32_16x16x32_bf16 v[100:103], v[156:159], v[172:175], v[100:103]
	v_mfma_f32_16x16x32_bf16 v[88:91], v[148:151], v[164:167], v[88:91]
	v_mfma_f32_16x16x32_bf16 v[84:87], v[156:159], v[164:167], v[84:87]
	v_mfma_f32_16x16x32_bf16 v[128:131], v[152:155], v[192:195], v[128:131]
	v_mfma_f32_16x16x32_bf16 v[124:127], v[160:163], v[192:195], v[124:127]
	v_mfma_f32_16x16x32_bf16 v[120:123], v[152:155], v[184:187], v[120:123]
	v_mfma_f32_16x16x32_bf16 v[116:119], v[160:163], v[184:187], v[116:119]
	v_mfma_f32_16x16x32_bf16 v[104:107], v[152:155], v[176:179], v[104:107]
	v_mfma_f32_16x16x32_bf16 v[100:103], v[160:163], v[176:179], v[100:103]
	v_mfma_f32_16x16x32_bf16 v[88:91], v[152:155], v[168:171], v[88:91]
	v_mfma_f32_16x16x32_bf16 v[84:87], v[160:163], v[168:171], v[84:87]
	s_setprio 0
	v_cmp_ne_u32_e64 s[2:3], 1, v217
	s_andn2_b64 vcc, exec, s[26:27]
	s_setprio 1
	v_mfma_f32_16x16x32_bf16 v[112:115], v[132:135], v[188:191], v[112:115]
	v_mfma_f32_16x16x32_bf16 v[108:111], v[140:143], v[188:191], v[108:111]
	v_mfma_f32_16x16x32_bf16 v[96:99], v[132:135], v[180:183], v[96:99]
	v_mfma_f32_16x16x32_bf16 v[92:95], v[140:143], v[180:183], v[92:95]
	v_mfma_f32_16x16x32_bf16 v[80:83], v[132:135], v[172:175], v[80:83]
	v_mfma_f32_16x16x32_bf16 v[76:79], v[140:143], v[172:175], v[76:79]
	v_mfma_f32_16x16x32_bf16 v[72:75], v[132:135], v[164:167], v[72:75]
	v_mfma_f32_16x16x32_bf16 v[68:71], v[140:143], v[164:167], v[68:71]
	v_mfma_f32_16x16x32_bf16 v[112:115], v[136:139], v[192:195], v[112:115]
	v_mfma_f32_16x16x32_bf16 v[108:111], v[144:147], v[192:195], v[108:111]
	v_mfma_f32_16x16x32_bf16 v[96:99], v[136:139], v[184:187], v[96:99]
	v_mfma_f32_16x16x32_bf16 v[92:95], v[144:147], v[184:187], v[92:95]
	v_mfma_f32_16x16x32_bf16 v[80:83], v[136:139], v[176:179], v[80:83]
	v_mfma_f32_16x16x32_bf16 v[76:79], v[144:147], v[176:179], v[76:79]
	v_mfma_f32_16x16x32_bf16 v[72:75], v[136:139], v[168:171], v[72:75]
	v_mfma_f32_16x16x32_bf16 v[68:71], v[144:147], v[168:171], v[68:71]
	s_setprio 0
.LBB0_1134:
	s_add_u32 s56, s34, 0xfff80080
	s_addc_u32 s57, s35, -1
	s_cmp_eq_u32 s77, 12
	s_cselect_b32 s59, s39, s57
	s_cselect_b32 s58, s38, s56
	s_cselect_b32 s57, s47, s41
	s_cselect_b32 s56, s46, s18
	s_barrier
	s_mov_b32 m0, s49
	v_lshl_add_u64 v[2:3], s[56:57], 0, v[198:199]
	s_add_u32 s78, s56, 0x80000
	ds_read_b128 v[188:191], v216 offset:16384
	ds_read_b128 v[192:195], v216 offset:17408
	ds_read_b128 v[180:183], v216 offset:18432
	ds_read_b128 v[184:187], v216 offset:19456
	ds_read_b128 v[172:175], v216 offset:20480
	ds_read_b128 v[176:179], v216 offset:21504
	ds_read_b128 v[164:167], v216 offset:22528
	ds_read_b128 v[168:171], v216 offset:23552
	global_load_lds_dwordx4 v[2:3], off
	v_lshl_add_u64 v[204:205], s[56:57], 0, v[196:197]
	s_mov_b32 m0, s50
	s_addc_u32 s79, s57, 0
	global_load_lds_dwordx4 v[204:205], off
	v_lshl_add_u64 v[206:207], s[78:79], 0, v[198:199]
	s_mov_b32 m0, s51
	v_lshl_add_u64 v[208:209], s[58:59], 0, v[196:197]
	global_load_lds_dwordx4 v[206:207], off
	v_lshl_add_u64 v[206:207], s[78:79], 0, v[196:197]
	s_mov_b32 m0, s60
	s_and_b64 vcc, exec, s[2:3]
	global_load_lds_dwordx4 v[206:207], off
	v_lshl_add_u64 v[206:207], s[58:59], 0, v[198:199]
	s_mov_b32 m0, s48
	s_nop 0
	global_load_lds_dwordx4 v[206:207], off
	s_mov_b32 m0, s61
	s_nop 0
	global_load_lds_dwordx4 v[208:209], off
	s_waitcnt vmcnt(8)
	s_waitcnt lgkmcnt(0)
	s_barrier
	s_setprio 1
	s_waitcnt lgkmcnt(0)
	v_mfma_f32_16x16x32_bf16 v[64:67], v[148:151], v[188:191], v[64:67]
	v_mfma_f32_16x16x32_bf16 v[60:63], v[156:159], v[188:191], v[60:63]
	v_mfma_f32_16x16x32_bf16 v[48:51], v[148:151], v[180:183], v[48:51]
	v_mfma_f32_16x16x32_bf16 v[44:47], v[156:159], v[180:183], v[44:47]
	v_mfma_f32_16x16x32_bf16 v[32:35], v[148:151], v[172:175], v[32:35]
	v_mfma_f32_16x16x32_bf16 v[28:31], v[156:159], v[172:175], v[28:31]
	v_mfma_f32_16x16x32_bf16 v[16:19], v[148:151], v[164:167], v[16:19]
	v_mfma_f32_16x16x32_bf16 v[12:15], v[156:159], v[164:167], v[12:15]
	v_mfma_f32_16x16x32_bf16 v[64:67], v[152:155], v[192:195], v[64:67]
	v_mfma_f32_16x16x32_bf16 v[60:63], v[160:163], v[192:195], v[60:63]
	v_mfma_f32_16x16x32_bf16 v[48:51], v[152:155], v[184:187], v[48:51]
	v_mfma_f32_16x16x32_bf16 v[44:47], v[160:163], v[184:187], v[44:47]
	v_mfma_f32_16x16x32_bf16 v[32:35], v[152:155], v[176:179], v[32:35]
	v_mfma_f32_16x16x32_bf16 v[28:31], v[160:163], v[176:179], v[28:31]
	v_mfma_f32_16x16x32_bf16 v[16:19], v[152:155], v[168:171], v[16:19]
	v_mfma_f32_16x16x32_bf16 v[12:15], v[160:163], v[168:171], v[12:15]
	s_setprio 0
	s_setprio 1
	v_mfma_f32_16x16x32_bf16 v[56:59], v[132:135], v[188:191], v[56:59]
	v_mfma_f32_16x16x32_bf16 v[52:55], v[140:143], v[188:191], v[52:55]
	v_mfma_f32_16x16x32_bf16 v[40:43], v[132:135], v[180:183], v[40:43]
	v_mfma_f32_16x16x32_bf16 v[36:39], v[140:143], v[180:183], v[36:39]
	v_mfma_f32_16x16x32_bf16 v[24:27], v[132:135], v[172:175], v[24:27]
	v_mfma_f32_16x16x32_bf16 v[20:23], v[140:143], v[172:175], v[20:23]
	v_mfma_f32_16x16x32_bf16 v[8:11], v[132:135], v[164:167], v[8:11]
	v_mfma_f32_16x16x32_bf16 v[4:7], v[140:143], v[164:167], v[4:7]
	v_mfma_f32_16x16x32_bf16 v[56:59], v[136:139], v[192:195], v[56:59]
	v_mfma_f32_16x16x32_bf16 v[52:55], v[144:147], v[192:195], v[52:55]
	v_mfma_f32_16x16x32_bf16 v[40:43], v[136:139], v[184:187], v[40:43]
	v_mfma_f32_16x16x32_bf16 v[36:39], v[144:147], v[184:187], v[36:39]
	v_mfma_f32_16x16x32_bf16 v[24:27], v[136:139], v[176:179], v[24:27]
	v_mfma_f32_16x16x32_bf16 v[20:23], v[144:147], v[176:179], v[20:23]
	v_mfma_f32_16x16x32_bf16 v[8:11], v[136:139], v[168:171], v[8:11]
	v_mfma_f32_16x16x32_bf16 v[4:7], v[144:147], v[168:171], v[4:7]
	s_setprio 0
.LBB0_1136:
	s_barrier
	v_add_u32_e32 v1, 0x18000, v213
	ds_read_b128 v[148:151], v1
	ds_read_b128 v[152:155], v1 offset:1024
	ds_read_b128 v[156:159], v1 offset:2048
	ds_read_b128 v[160:163], v1 offset:3072
	v_add_u32_e32 v1, 0x1c000, v213
	ds_read_b128 v[132:135], v1
	ds_read_b128 v[136:139], v1 offset:1024
	ds_read_b128 v[140:143], v1 offset:2048
	ds_read_b128 v[144:147], v1 offset:3072
	s_add_u32 s58, s58, 0x80000
	s_addc_u32 s59, s59, 0
	s_mov_b32 m0, s62
	v_lshl_add_u64 v[218:219], s[58:59], 0, v[198:199]
	s_waitcnt lgkmcnt(0)
	ds_read_b128 v[188:191], v216 offset:32768
	ds_read_b128 v[192:195], v216 offset:33792
	ds_read_b128 v[180:183], v216 offset:34816
	ds_read_b128 v[184:187], v216 offset:35840
	ds_read_b128 v[172:175], v216 offset:36864
	ds_read_b128 v[176:179], v216 offset:37888
	ds_read_b128 v[164:167], v216 offset:38912
	ds_read_b128 v[168:171], v216 offset:39936
	global_load_lds_dwordx4 v[218:219], off
	v_lshl_add_u64 v[218:219], s[58:59], 0, v[196:197]
	s_mov_b32 m0, s63
	s_nop 0
	global_load_lds_dwordx4 v[218:219], off
	s_waitcnt vmcnt(8)
	s_waitcnt lgkmcnt(0)
	s_barrier
	s_setprio 1
	s_waitcnt lgkmcnt(0)
	v_mfma_f32_16x16x32_bf16 v[128:131], v[148:151], v[188:191], v[128:131]
	v_mfma_f32_16x16x32_bf16 v[124:127], v[156:159], v[188:191], v[124:127]
	v_mfma_f32_16x16x32_bf16 v[120:123], v[148:151], v[180:183], v[120:123]
	v_mfma_f32_16x16x32_bf16 v[116:119], v[156:159], v[180:183], v[116:119]
	v_mfma_f32_16x16x32_bf16 v[104:107], v[148:151], v[172:175], v[104:107]
	v_mfma_f32_16x16x32_bf16 v[100:103], v[156:159], v[172:175], v[100:103]
	v_mfma_f32_16x16x32_bf16 v[88:91], v[148:151], v[164:167], v[88:91]
	v_mfma_f32_16x16x32_bf16 v[84:87], v[156:159], v[164:167], v[84:87]
	v_mfma_f32_16x16x32_bf16 v[128:131], v[152:155], v[192:195], v[128:131]
	v_mfma_f32_16x16x32_bf16 v[124:127], v[160:163], v[192:195], v[124:127]
	v_mfma_f32_16x16x32_bf16 v[120:123], v[152:155], v[184:187], v[120:123]
	v_mfma_f32_16x16x32_bf16 v[116:119], v[160:163], v[184:187], v[116:119]
	v_mfma_f32_16x16x32_bf16 v[104:107], v[152:155], v[176:179], v[104:107]
	v_mfma_f32_16x16x32_bf16 v[100:103], v[160:163], v[176:179], v[100:103]
	v_mfma_f32_16x16x32_bf16 v[88:91], v[152:155], v[168:171], v[88:91]
	v_mfma_f32_16x16x32_bf16 v[84:87], v[160:163], v[168:171], v[84:87]
	s_setprio 0
	s_and_b64 vcc, exec, s[2:3]
	s_setprio 1
	v_mfma_f32_16x16x32_bf16 v[112:115], v[132:135], v[188:191], v[112:115]
	v_mfma_f32_16x16x32_bf16 v[108:111], v[140:143], v[188:191], v[108:111]
	v_mfma_f32_16x16x32_bf16 v[96:99], v[132:135], v[180:183], v[96:99]
	v_mfma_f32_16x16x32_bf16 v[92:95], v[140:143], v[180:183], v[92:95]
	v_mfma_f32_16x16x32_bf16 v[80:83], v[132:135], v[172:175], v[80:83]
	v_mfma_f32_16x16x32_bf16 v[76:79], v[140:143], v[172:175], v[76:79]
	v_mfma_f32_16x16x32_bf16 v[72:75], v[132:135], v[164:167], v[72:75]
	v_mfma_f32_16x16x32_bf16 v[68:71], v[140:143], v[164:167], v[68:71]
	v_mfma_f32_16x16x32_bf16 v[112:115], v[136:139], v[192:195], v[112:115]
	v_mfma_f32_16x16x32_bf16 v[108:111], v[144:147], v[192:195], v[108:111]
	v_mfma_f32_16x16x32_bf16 v[96:99], v[136:139], v[184:187], v[96:99]
	v_mfma_f32_16x16x32_bf16 v[92:95], v[144:147], v[184:187], v[92:95]
	v_mfma_f32_16x16x32_bf16 v[80:83], v[136:139], v[176:179], v[80:83]
	v_mfma_f32_16x16x32_bf16 v[76:79], v[144:147], v[176:179], v[76:79]
	v_mfma_f32_16x16x32_bf16 v[72:75], v[136:139], v[168:171], v[72:75]
	v_mfma_f32_16x16x32_bf16 v[68:71], v[144:147], v[168:171], v[68:71]
	s_setprio 0
.LBB0_1138:
	s_barrier
	s_mov_b32 m0, s66
	v_lshl_add_u64 v[2:3], v[2:3], 0, s[16:17]
	s_add_u32 s56, s56, 0x80080
	ds_read_b128 v[188:191], v216 offset:49152
	ds_read_b128 v[192:195], v216 offset:50176
	ds_read_b128 v[180:183], v216 offset:51200
	ds_read_b128 v[184:187], v216 offset:52224
	ds_read_b128 v[172:175], v216 offset:53248
	ds_read_b128 v[176:179], v216 offset:54272
	ds_read_b128 v[164:167], v216 offset:55296
	ds_read_b128 v[168:171], v216 offset:56320
	global_load_lds_dwordx4 v[2:3], off
	v_lshl_add_u64 v[2:3], v[204:205], 0, s[16:17]
	s_mov_b32 m0, s67
	s_addc_u32 s57, s57, 0
	global_load_lds_dwordx4 v[2:3], off
	v_lshl_add_u64 v[2:3], s[56:57], 0, v[198:199]
	s_mov_b32 m0, s70
	s_and_b64 vcc, exec, s[2:3]
	global_load_lds_dwordx4 v[2:3], off
	v_lshl_add_u64 v[2:3], s[56:57], 0, v[196:197]
	s_mov_b32 m0, s71
	s_nop 0
	global_load_lds_dwordx4 v[2:3], off
	v_lshl_add_u64 v[2:3], v[206:207], 0, s[16:17]
	s_mov_b32 m0, s68
	s_nop 0
	global_load_lds_dwordx4 v[2:3], off
	v_lshl_add_u64 v[2:3], v[208:209], 0, s[16:17]
	s_mov_b32 m0, s69
	s_nop 0
	global_load_lds_dwordx4 v[2:3], off
	s_waitcnt vmcnt(8)
	s_waitcnt lgkmcnt(0)
	s_barrier
	s_setprio 1
	s_waitcnt lgkmcnt(0)
	v_mfma_f32_16x16x32_bf16 v[64:67], v[148:151], v[188:191], v[64:67]
	v_mfma_f32_16x16x32_bf16 v[60:63], v[156:159], v[188:191], v[60:63]
	v_mfma_f32_16x16x32_bf16 v[48:51], v[148:151], v[180:183], v[48:51]
	v_mfma_f32_16x16x32_bf16 v[44:47], v[156:159], v[180:183], v[44:47]
	v_mfma_f32_16x16x32_bf16 v[32:35], v[148:151], v[172:175], v[32:35]
	v_mfma_f32_16x16x32_bf16 v[28:31], v[156:159], v[172:175], v[28:31]
	v_mfma_f32_16x16x32_bf16 v[16:19], v[148:151], v[164:167], v[16:19]
	v_mfma_f32_16x16x32_bf16 v[12:15], v[156:159], v[164:167], v[12:15]
	v_mfma_f32_16x16x32_bf16 v[64:67], v[152:155], v[192:195], v[64:67]
	v_mfma_f32_16x16x32_bf16 v[60:63], v[160:163], v[192:195], v[60:63]
	v_mfma_f32_16x16x32_bf16 v[48:51], v[152:155], v[184:187], v[48:51]
	v_mfma_f32_16x16x32_bf16 v[44:47], v[160:163], v[184:187], v[44:47]
	v_mfma_f32_16x16x32_bf16 v[32:35], v[152:155], v[176:179], v[32:35]
	v_mfma_f32_16x16x32_bf16 v[28:31], v[160:163], v[176:179], v[28:31]
	v_mfma_f32_16x16x32_bf16 v[16:19], v[152:155], v[168:171], v[16:19]
	v_mfma_f32_16x16x32_bf16 v[12:15], v[160:163], v[168:171], v[12:15]
	s_setprio 0
	s_setprio 1
	v_mfma_f32_16x16x32_bf16 v[56:59], v[132:135], v[188:191], v[56:59]
	v_mfma_f32_16x16x32_bf16 v[52:55], v[140:143], v[188:191], v[52:55]
	v_mfma_f32_16x16x32_bf16 v[40:43], v[132:135], v[180:183], v[40:43]
	v_mfma_f32_16x16x32_bf16 v[36:39], v[140:143], v[180:183], v[36:39]
	v_mfma_f32_16x16x32_bf16 v[24:27], v[132:135], v[172:175], v[24:27]
	v_mfma_f32_16x16x32_bf16 v[20:23], v[140:143], v[172:175], v[20:23]
	v_mfma_f32_16x16x32_bf16 v[8:11], v[132:135], v[164:167], v[8:11]
	v_mfma_f32_16x16x32_bf16 v[2:5], v[140:143], v[164:167], v[4:7]
	v_mfma_f32_16x16x32_bf16 v[56:59], v[136:139], v[192:195], v[56:59]
	v_mfma_f32_16x16x32_bf16 v[52:55], v[144:147], v[192:195], v[52:55]
	v_mfma_f32_16x16x32_bf16 v[40:43], v[136:139], v[184:187], v[40:43]
	v_mfma_f32_16x16x32_bf16 v[36:39], v[144:147], v[184:187], v[36:39]
	v_mfma_f32_16x16x32_bf16 v[24:27], v[136:139], v[176:179], v[24:27]
	v_mfma_f32_16x16x32_bf16 v[20:23], v[144:147], v[176:179], v[20:23]
	v_mfma_f32_16x16x32_bf16 v[8:11], v[136:139], v[168:171], v[8:11]
	v_mfma_f32_16x16x32_bf16 v[4:7], v[144:147], v[168:171], v[2:5]
	s_setprio 0
	s_branch .LBB0_1131
.Lq5_entry:
	v_mov_b32_e32 v4, 0
	v_mov_b32_e32 v5, 0
	v_mov_b32_e32 v6, 0
	v_mov_b32_e32 v7, 0
	v_mov_b32_e32 v8, 0
	v_mov_b32_e32 v9, 0
	v_mov_b32_e32 v10, 0
	v_mov_b32_e32 v11, 0
	v_mov_b32_e32 v12, 0
	v_mov_b32_e32 v13, 0
	v_mov_b32_e32 v14, 0
	v_mov_b32_e32 v15, 0
	v_mov_b32_e32 v16, 0
	v_mov_b32_e32 v17, 0
	v_mov_b32_e32 v18, 0
	v_mov_b32_e32 v19, 0
	v_mov_b32_e32 v20, 0
	v_mov_b32_e32 v21, 0
	v_mov_b32_e32 v22, 0
	v_mov_b32_e32 v23, 0
	v_mov_b32_e32 v24, 0
	v_mov_b32_e32 v25, 0
	v_mov_b32_e32 v26, 0
	v_mov_b32_e32 v27, 0
	v_mov_b32_e32 v28, 0
	v_mov_b32_e32 v29, 0
	v_mov_b32_e32 v30, 0
	v_mov_b32_e32 v31, 0
	v_mov_b32_e32 v32, 0
	v_mov_b32_e32 v33, 0
	v_mov_b32_e32 v34, 0
	v_mov_b32_e32 v35, 0
	v_mov_b32_e32 v36, 0
	v_mov_b32_e32 v37, 0
	v_mov_b32_e32 v38, 0
	v_mov_b32_e32 v39, 0
	v_mov_b32_e32 v40, 0
	v_mov_b32_e32 v41, 0
	v_mov_b32_e32 v42, 0
	v_mov_b32_e32 v43, 0
	v_mov_b32_e32 v44, 0
	v_mov_b32_e32 v45, 0
	v_mov_b32_e32 v46, 0
	v_mov_b32_e32 v47, 0
	v_mov_b32_e32 v48, 0
	v_mov_b32_e32 v49, 0
	v_mov_b32_e32 v50, 0
	v_mov_b32_e32 v51, 0
	v_cmp_ne_u32_e64 s[2:3], 1, v217
	s_andn2_b64 vcc, exec, s[26:27]
	s_add_u32 s56, s34, 0xfff80080
	s_addc_u32 s57, s35, -1
	s_cmp_eq_u32 s77, 12
	s_cselect_b32 s59, s39, s57
	s_cselect_b32 s58, s38, s56
	s_cselect_b32 s57, s47, s41
	s_cselect_b32 s56, s46, s18
	s_mov_b32 m0, s51
	v_lshl_add_u64 v[2:3], s[56:57], 0, v[198:199]
	s_add_u32 s78, s56, 0x80000
	global_load_lds_dwordx4 v[2:3], off
	v_lshl_add_u64 v[204:205], s[56:57], 0, v[196:197]
	s_mov_b32 m0, s60
	s_addc_u32 s79, s57, 0
	global_load_lds_dwordx4 v[204:205], off
	v_lshl_add_u64 v[206:207], s[78:79], 0, v[198:199]
	s_mov_b32 m0, s66
	v_lshl_add_u64 v[208:209], s[58:59], 0, v[196:197]
	v_lshl_add_u64 v[206:207], s[78:79], 0, v[196:197]
	s_mov_b32 m0, s67
	s_and_b64 vcc, exec, s[2:3]
	v_lshl_add_u64 v[206:207], s[58:59], 0, v[198:199]
	s_mov_b32 m0, s62
	s_nop 0
	global_load_lds_dwordx4 v[206:207], off
	s_mov_b32 m0, s63
	s_nop 0
	global_load_lds_dwordx4 v[208:209], off
	s_and_b64 vcc, exec, s[2:3]
	s_mov_b32 m0, s70
	v_lshl_add_u64 v[2:3], v[2:3], 0, s[16:17]
	s_add_u32 s56, s56, 0x80080
	global_load_lds_dwordx4 v[2:3], off
	v_lshl_add_u64 v[2:3], v[204:205], 0, s[16:17]
	s_mov_b32 m0, s71
	s_addc_u32 s57, s57, 0
	global_load_lds_dwordx4 v[2:3], off
	v_lshl_add_u64 v[2:3], s[56:57], 0, v[198:199]
	s_add_i32 m0, s48, 0x20000
	s_and_b64 vcc, exec, s[2:3]
	v_lshl_add_u64 v[2:3], s[56:57], 0, v[196:197]
	s_add_i32 m0, s48, 0x22000
	s_nop 0
	v_lshl_add_u64 v[2:3], v[206:207], 0, s[16:17]
	s_add_i32 m0, s48, 0xc000
	s_nop 0
	global_load_lds_dwordx4 v[2:3], off
	v_lshl_add_u64 v[2:3], v[208:209], 0, s[16:17]
	s_add_i32 m0, s48, 0xe000
	s_nop 0
	global_load_lds_dwordx4 v[2:3], off
	s_add_u32 s34, s34, 0x100
	s_addc_u32 s35, s35, 0
	s_add_u32 s18, s18, 0x100
	s_addc_u32 s41, s41, 0
	s_branch .Lq5_top
	s_nop 0
	s_nop 0
.Lq5_be:
	s_barrier
	s_add_i32 s77, s77, 2
	s_add_u32 s34, s34, 0x100
	s_addc_u32 s35, s35, 0
	s_add_u32 s18, s18, 0x100
	s_addc_u32 s41, s41, 0
	s_cmp_gt_u32 s77, 13
	s_cbranch_scc1 .Lq5_exit

.LBB0_1283:
	s_andn2_b64 vcc, exec, s[34:35]
	s_cbranch_vccnz .Lq6_entry
	ds_read_b128 v[180:183], v247
	ds_read_b128 v[184:187], v247 offset:1024
	ds_read_b128 v[188:191], v247 offset:2048
	ds_read_b128 v[192:195], v247 offset:3072
	ds_read_b128 v[164:167], v248
	ds_read_b128 v[168:171], v248 offset:1024
	ds_read_b128 v[172:175], v248 offset:2048
	ds_read_b128 v[176:179], v248 offset:3072
	v_lshl_add_u64 v[2:3], s[38:39], 0, v[232:233]
	s_add_i32 m0, s44, 0xc000
	ds_read_b128 v[220:223], v249
	ds_read_b128 v[224:227], v249 offset:1024
	ds_read_b128 v[212:215], v249 offset:2048
	ds_read_b128 v[216:219], v249 offset:3072
	ds_read_b128 v[204:207], v249 offset:4096
	ds_read_b128 v[208:211], v249 offset:5120
	ds_read_b128 v[196:199], v249 offset:6144
	ds_read_b128 v[200:203], v249 offset:7168
	global_load_lds_dwordx4 v[2:3], off
	v_lshl_add_u64 v[2:3], s[38:39], 0, v[234:235]
	s_add_i32 m0, s44, 0xe000
	s_nop 0
	global_load_lds_dwordx4 v[2:3], off
	s_waitcnt vmcnt(8)
	s_waitcnt lgkmcnt(0)
	s_barrier
	s_setprio 1
	s_waitcnt lgkmcnt(0)
	v_mfma_f32_16x16x32_bf16 v[68:71], v[180:183], v[220:223], v[160:163]
	v_mfma_f32_16x16x32_bf16 v[72:75], v[188:191], v[220:223], v[156:159]
	v_mfma_f32_16x16x32_bf16 v[76:79], v[180:183], v[212:215], v[152:155]
	v_mfma_f32_16x16x32_bf16 v[80:83], v[188:191], v[212:215], v[148:151]
	v_mfma_f32_16x16x32_bf16 v[84:87], v[180:183], v[204:207], v[136:139]
	v_mfma_f32_16x16x32_bf16 v[92:95], v[188:191], v[204:207], v[132:135]
	v_mfma_f32_16x16x32_bf16 v[96:99], v[180:183], v[196:199], v[120:123]
	v_mfma_f32_16x16x32_bf16 v[100:103], v[188:191], v[196:199], v[112:115]
	v_mfma_f32_16x16x32_bf16 v[68:71], v[184:187], v[224:227], v[68:71]
	v_mfma_f32_16x16x32_bf16 v[72:75], v[192:195], v[224:227], v[72:75]
	v_mfma_f32_16x16x32_bf16 v[76:79], v[184:187], v[216:219], v[76:79]
	v_mfma_f32_16x16x32_bf16 v[80:83], v[192:195], v[216:219], v[80:83]
	v_mfma_f32_16x16x32_bf16 v[84:87], v[184:187], v[208:211], v[84:87]
	v_mfma_f32_16x16x32_bf16 v[92:95], v[192:195], v[208:211], v[92:95]
	v_mfma_f32_16x16x32_bf16 v[96:99], v[184:187], v[200:203], v[96:99]
	v_mfma_f32_16x16x32_bf16 v[100:103], v[192:195], v[200:203], v[100:103]
	s_setprio 0
	v_cmp_ne_u32_e64 s[4:5], 1, v251
	s_andn2_b64 vcc, exec, s[34:35]
	s_setprio 1
	v_mfma_f32_16x16x32_bf16 v[112:115], v[164:167], v[220:223], v[144:147]
	v_mfma_f32_16x16x32_bf16 v[144:147], v[168:171], v[224:227], v[112:115]
	v_mfma_f32_16x16x32_bf16 v[112:115], v[172:175], v[220:223], v[140:143]
	v_mfma_f32_16x16x32_bf16 v[140:143], v[176:179], v[224:227], v[112:115]
	v_mfma_f32_16x16x32_bf16 v[112:115], v[164:167], v[212:215], v[128:131]
	v_mfma_f32_16x16x32_bf16 v[128:131], v[168:171], v[216:219], v[112:115]
	v_mfma_f32_16x16x32_bf16 v[112:115], v[172:175], v[212:215], v[124:127]
	v_mfma_f32_16x16x32_bf16 v[124:127], v[176:179], v[216:219], v[112:115]
	v_mfma_f32_16x16x32_bf16 v[112:115], v[164:167], v[204:207], v[116:119]
	v_mfma_f32_16x16x32_bf16 v[108:111], v[172:175], v[204:207], v[108:111]
	v_mfma_f32_16x16x32_bf16 v[104:107], v[164:167], v[196:199], v[104:107]
	v_mfma_f32_16x16x32_bf16 v[88:91], v[172:175], v[196:199], v[88:91]
	v_mfma_f32_16x16x32_bf16 v[116:119], v[168:171], v[208:211], v[112:115]
	v_mfma_f32_16x16x32_bf16 v[108:111], v[176:179], v[208:211], v[108:111]
	v_mfma_f32_16x16x32_bf16 v[104:107], v[168:171], v[200:203], v[104:107]
	v_mfma_f32_16x16x32_bf16 v[88:91], v[176:179], v[200:203], v[88:91]
	s_setprio 0
.LBB0_1285:
	s_add_u32 s40, s38, 0xfff80080
	s_addc_u32 s41, s39, -1
	s_cmp_eq_u32 s84, 28
	s_cselect_b32 s47, s29, s41
	s_cselect_b32 s46, s28, s40
	s_cselect_b32 s41, s37, s27
	s_cselect_b32 s40, s36, s16
	s_barrier
	s_mov_b32 m0, s45
	v_lshl_add_u64 v[2:3], s[40:41], 0, v[230:231]
	s_add_u32 s86, s40, 0x80000
	ds_read_b128 v[156:159], v249 offset:16384
	ds_read_b128 v[160:163], v249 offset:17408
	ds_read_b128 v[148:151], v249 offset:18432
	ds_read_b128 v[152:155], v249 offset:19456
	ds_read_b128 v[132:135], v249 offset:20480
	ds_read_b128 v[136:139], v249 offset:21504
	ds_read_b128 v[112:115], v249 offset:22528
	ds_read_b128 v[120:123], v249 offset:23552
	global_load_lds_dwordx4 v[2:3], off
	v_lshl_add_u64 v[236:237], s[40:41], 0, v[228:229]
	s_mov_b32 m0, s48
	s_addc_u32 s87, s41, 0
	global_load_lds_dwordx4 v[236:237], off
	v_lshl_add_u64 v[196:197], s[86:87], 0, v[230:231]
	s_mov_b32 m0, s49
	v_lshl_add_u64 v[238:239], s[46:47], 0, v[230:231]
	global_load_lds_dwordx4 v[196:197], off
	v_lshl_add_u64 v[196:197], s[86:87], 0, v[228:229]
	s_mov_b32 m0, s50
	v_lshl_add_u64 v[240:241], s[46:47], 0, v[228:229]
	global_load_lds_dwordx4 v[196:197], off
	s_mov_b32 m0, s44
	s_and_b64 vcc, exec, s[4:5]
	global_load_lds_dwordx4 v[238:239], off
	s_mov_b32 m0, s51
	s_nop 0
	global_load_lds_dwordx4 v[240:241], off
	s_waitcnt vmcnt(8)
	s_waitcnt lgkmcnt(0)
	s_barrier
	s_setprio 1
	s_waitcnt lgkmcnt(0)
	v_mfma_f32_16x16x32_bf16 v[64:67], v[180:183], v[156:159], v[64:67]
	v_mfma_f32_16x16x32_bf16 v[60:63], v[188:191], v[156:159], v[60:63]
	v_mfma_f32_16x16x32_bf16 v[48:51], v[180:183], v[148:151], v[48:51]
	v_mfma_f32_16x16x32_bf16 v[44:47], v[188:191], v[148:151], v[44:47]
	v_mfma_f32_16x16x32_bf16 v[32:35], v[180:183], v[132:135], v[32:35]
	v_mfma_f32_16x16x32_bf16 v[28:31], v[188:191], v[132:135], v[28:31]
	v_mfma_f32_16x16x32_bf16 v[16:19], v[180:183], v[112:115], v[16:19]
	v_mfma_f32_16x16x32_bf16 v[12:15], v[188:191], v[112:115], v[12:15]
	v_mfma_f32_16x16x32_bf16 v[64:67], v[184:187], v[160:163], v[64:67]
	v_mfma_f32_16x16x32_bf16 v[60:63], v[192:195], v[160:163], v[60:63]
	v_mfma_f32_16x16x32_bf16 v[48:51], v[184:187], v[152:155], v[48:51]
	v_mfma_f32_16x16x32_bf16 v[44:47], v[192:195], v[152:155], v[44:47]
	v_mfma_f32_16x16x32_bf16 v[32:35], v[184:187], v[136:139], v[32:35]
	v_mfma_f32_16x16x32_bf16 v[28:31], v[192:195], v[136:139], v[28:31]
	v_mfma_f32_16x16x32_bf16 v[16:19], v[184:187], v[120:123], v[16:19]
	v_mfma_f32_16x16x32_bf16 v[12:15], v[192:195], v[120:123], v[12:15]
	s_setprio 0
	s_setprio 1
	v_mfma_f32_16x16x32_bf16 v[56:59], v[164:167], v[156:159], v[56:59]
	v_mfma_f32_16x16x32_bf16 v[52:55], v[172:175], v[156:159], v[52:55]
	v_mfma_f32_16x16x32_bf16 v[40:43], v[164:167], v[148:151], v[40:43]
	v_mfma_f32_16x16x32_bf16 v[36:39], v[172:175], v[148:151], v[36:39]
	v_mfma_f32_16x16x32_bf16 v[24:27], v[164:167], v[132:135], v[24:27]
	v_mfma_f32_16x16x32_bf16 v[20:23], v[172:175], v[132:135], v[20:23]
	v_mfma_f32_16x16x32_bf16 v[8:11], v[164:167], v[112:115], v[8:11]
	v_mfma_f32_16x16x32_bf16 v[4:7], v[172:175], v[112:115], v[4:7]
	v_mfma_f32_16x16x32_bf16 v[56:59], v[168:171], v[160:163], v[56:59]
	v_mfma_f32_16x16x32_bf16 v[52:55], v[176:179], v[160:163], v[52:55]
	v_mfma_f32_16x16x32_bf16 v[40:43], v[168:171], v[152:155], v[40:43]
	v_mfma_f32_16x16x32_bf16 v[36:39], v[176:179], v[152:155], v[36:39]
	v_mfma_f32_16x16x32_bf16 v[24:27], v[168:171], v[136:139], v[24:27]
	v_mfma_f32_16x16x32_bf16 v[20:23], v[176:179], v[136:139], v[20:23]
	v_mfma_f32_16x16x32_bf16 v[8:11], v[168:171], v[120:123], v[8:11]
	v_mfma_f32_16x16x32_bf16 v[4:7], v[176:179], v[120:123], v[4:7]
	s_setprio 0
.LBB0_1287:
	s_barrier
	v_add_u32_e32 v1, 0x18000, v246
	ds_read_b128 v[180:183], v1
	ds_read_b128 v[184:187], v1 offset:1024
	ds_read_b128 v[188:191], v1 offset:2048
	ds_read_b128 v[192:195], v1 offset:3072
	v_add_u32_e32 v1, 0x1c000, v246
	ds_read_b128 v[164:167], v1
	ds_read_b128 v[168:171], v1 offset:1024
	ds_read_b128 v[172:175], v1 offset:2048
	ds_read_b128 v[176:179], v1 offset:3072
	s_add_u32 s46, s46, 0x80000
	s_addc_u32 s47, s47, 0
	s_mov_b32 m0, s56
	s_waitcnt lgkmcnt(0)
	v_lshl_add_u64 v[112:113], s[46:47], 0, v[230:231]
	ds_read_b128 v[220:223], v249 offset:32768
	ds_read_b128 v[224:227], v249 offset:33792
	ds_read_b128 v[212:215], v249 offset:34816
	ds_read_b128 v[216:219], v249 offset:35840
	ds_read_b128 v[204:207], v249 offset:36864
	ds_read_b128 v[208:211], v249 offset:37888
	ds_read_b128 v[196:199], v249 offset:38912
	ds_read_b128 v[200:203], v249 offset:39936
	global_load_lds_dwordx4 v[112:113], off
	v_lshl_add_u64 v[112:113], s[46:47], 0, v[228:229]
	s_mov_b32 m0, s57
	s_nop 0
	global_load_lds_dwordx4 v[112:113], off
	s_waitcnt vmcnt(8)
	s_waitcnt lgkmcnt(0)
	s_barrier
	s_setprio 1
	s_waitcnt lgkmcnt(0)
	v_mfma_f32_16x16x32_bf16 v[68:71], v[180:183], v[220:223], v[68:71]
	v_mfma_f32_16x16x32_bf16 v[160:163], v[184:187], v[224:227], v[68:71]
	v_mfma_f32_16x16x32_bf16 v[68:71], v[188:191], v[220:223], v[72:75]
	v_mfma_f32_16x16x32_bf16 v[156:159], v[192:195], v[224:227], v[68:71]
	v_mfma_f32_16x16x32_bf16 v[68:71], v[180:183], v[212:215], v[76:79]
	v_mfma_f32_16x16x32_bf16 v[152:155], v[184:187], v[216:219], v[68:71]
	v_mfma_f32_16x16x32_bf16 v[68:71], v[188:191], v[212:215], v[80:83]
	v_mfma_f32_16x16x32_bf16 v[148:151], v[192:195], v[216:219], v[68:71]
	v_mfma_f32_16x16x32_bf16 v[68:71], v[180:183], v[204:207], v[84:87]
	v_mfma_f32_16x16x32_bf16 v[136:139], v[184:187], v[208:211], v[68:71]
	v_mfma_f32_16x16x32_bf16 v[68:71], v[188:191], v[204:207], v[92:95]
	v_mfma_f32_16x16x32_bf16 v[132:135], v[192:195], v[208:211], v[68:71]
	v_mfma_f32_16x16x32_bf16 v[68:71], v[180:183], v[196:199], v[96:99]
	v_mfma_f32_16x16x32_bf16 v[120:123], v[184:187], v[200:203], v[68:71]
	v_mfma_f32_16x16x32_bf16 v[68:71], v[188:191], v[196:199], v[100:103]
	v_mfma_f32_16x16x32_bf16 v[112:115], v[192:195], v[200:203], v[68:71]
	s_setprio 0
	s_and_b64 vcc, exec, s[4:5]
	s_setprio 1
	v_mfma_f32_16x16x32_bf16 v[68:71], v[164:167], v[220:223], v[144:147]
	v_mfma_f32_16x16x32_bf16 v[144:147], v[168:171], v[224:227], v[68:71]
	v_mfma_f32_16x16x32_bf16 v[68:71], v[172:175], v[220:223], v[140:143]
	v_mfma_f32_16x16x32_bf16 v[140:143], v[176:179], v[224:227], v[68:71]
	v_mfma_f32_16x16x32_bf16 v[68:71], v[164:167], v[212:215], v[128:131]
	v_mfma_f32_16x16x32_bf16 v[128:131], v[168:171], v[216:219], v[68:71]
	v_mfma_f32_16x16x32_bf16 v[68:71], v[172:175], v[212:215], v[124:127]
	v_mfma_f32_16x16x32_bf16 v[124:127], v[176:179], v[216:219], v[68:71]
	v_mfma_f32_16x16x32_bf16 v[68:71], v[164:167], v[204:207], v[116:119]
	v_mfma_f32_16x16x32_bf16 v[116:119], v[168:171], v[208:211], v[68:71]
	v_mfma_f32_16x16x32_bf16 v[68:71], v[172:175], v[204:207], v[108:111]
	v_mfma_f32_16x16x32_bf16 v[108:111], v[176:179], v[208:211], v[68:71]
	v_mfma_f32_16x16x32_bf16 v[68:71], v[164:167], v[196:199], v[104:107]
	v_mfma_f32_16x16x32_bf16 v[104:107], v[168:171], v[200:203], v[68:71]
	v_mfma_f32_16x16x32_bf16 v[68:71], v[172:175], v[196:199], v[88:91]
	v_mfma_f32_16x16x32_bf16 v[88:91], v[176:179], v[200:203], v[68:71]
	s_setprio 0
.LBB0_1289:
	s_barrier
	s_mov_b32 m0, s61
	v_lshl_add_u64 v[2:3], v[2:3], 0, s[14:15]
	s_add_u32 s40, s40, 0x80080
	ds_read_b128 v[96:99], v249 offset:49152
	ds_read_b128 v[100:103], v249 offset:50176
	ds_read_b128 v[84:87], v249 offset:51200
	ds_read_b128 v[92:95], v249 offset:52224
	ds_read_b128 v[76:79], v249 offset:53248
	ds_read_b128 v[80:83], v249 offset:54272
	ds_read_b128 v[68:71], v249 offset:55296
	ds_read_b128 v[72:75], v249 offset:56320
	global_load_lds_dwordx4 v[2:3], off
	v_lshl_add_u64 v[2:3], v[236:237], 0, s[14:15]
	s_mov_b32 m0, s62
	s_addc_u32 s41, s41, 0
	global_load_lds_dwordx4 v[2:3], off
	v_lshl_add_u64 v[2:3], s[40:41], 0, v[230:231]
	s_mov_b32 m0, s65
	s_and_b64 vcc, exec, s[4:5]
	global_load_lds_dwordx4 v[2:3], off
	v_lshl_add_u64 v[2:3], s[40:41], 0, v[228:229]
	s_mov_b32 m0, s66
	s_nop 0
	global_load_lds_dwordx4 v[2:3], off
	v_lshl_add_u64 v[2:3], v[238:239], 0, s[14:15]
	s_mov_b32 m0, s63
	s_nop 0
	global_load_lds_dwordx4 v[2:3], off
	v_lshl_add_u64 v[2:3], v[240:241], 0, s[14:15]
	s_mov_b32 m0, s64
	s_nop 0
	global_load_lds_dwordx4 v[2:3], off
	s_waitcnt vmcnt(8)
	s_waitcnt lgkmcnt(0)
	s_barrier
	s_setprio 1
	s_waitcnt lgkmcnt(0)
	v_mfma_f32_16x16x32_bf16 v[64:67], v[180:183], v[96:99], v[64:67]
	v_mfma_f32_16x16x32_bf16 v[60:63], v[188:191], v[96:99], v[60:63]
	v_mfma_f32_16x16x32_bf16 v[48:51], v[180:183], v[84:87], v[48:51]
	v_mfma_f32_16x16x32_bf16 v[44:47], v[188:191], v[84:87], v[44:47]
	v_mfma_f32_16x16x32_bf16 v[32:35], v[180:183], v[76:79], v[32:35]
	v_mfma_f32_16x16x32_bf16 v[28:31], v[188:191], v[76:79], v[28:31]
	v_mfma_f32_16x16x32_bf16 v[16:19], v[180:183], v[68:71], v[16:19]
	v_mfma_f32_16x16x32_bf16 v[12:15], v[188:191], v[68:71], v[12:15]
	v_mfma_f32_16x16x32_bf16 v[64:67], v[184:187], v[100:103], v[64:67]
	v_mfma_f32_16x16x32_bf16 v[60:63], v[192:195], v[100:103], v[60:63]
	v_mfma_f32_16x16x32_bf16 v[48:51], v[184:187], v[92:95], v[48:51]
	v_mfma_f32_16x16x32_bf16 v[44:47], v[192:195], v[92:95], v[44:47]
	v_mfma_f32_16x16x32_bf16 v[32:35], v[184:187], v[80:83], v[32:35]
	v_mfma_f32_16x16x32_bf16 v[28:31], v[192:195], v[80:83], v[28:31]
	v_mfma_f32_16x16x32_bf16 v[16:19], v[184:187], v[72:75], v[16:19]
	v_mfma_f32_16x16x32_bf16 v[12:15], v[192:195], v[72:75], v[12:15]
	s_setprio 0
	s_setprio 1
	v_mfma_f32_16x16x32_bf16 v[56:59], v[164:167], v[96:99], v[56:59]
	v_mfma_f32_16x16x32_bf16 v[52:55], v[172:175], v[96:99], v[52:55]
	v_mfma_f32_16x16x32_bf16 v[40:43], v[164:167], v[84:87], v[40:43]
	v_mfma_f32_16x16x32_bf16 v[36:39], v[172:175], v[84:87], v[36:39]
	v_mfma_f32_16x16x32_bf16 v[24:27], v[164:167], v[76:79], v[24:27]
	v_mfma_f32_16x16x32_bf16 v[20:23], v[172:175], v[76:79], v[20:23]
	v_mfma_f32_16x16x32_bf16 v[8:11], v[164:167], v[68:71], v[8:11]
	v_mfma_f32_16x16x32_bf16 v[2:5], v[172:175], v[68:71], v[4:7]
	v_mfma_f32_16x16x32_bf16 v[56:59], v[168:171], v[100:103], v[56:59]
	v_mfma_f32_16x16x32_bf16 v[52:55], v[176:179], v[100:103], v[52:55]
	v_mfma_f32_16x16x32_bf16 v[40:43], v[168:171], v[92:95], v[40:43]
	v_mfma_f32_16x16x32_bf16 v[36:39], v[176:179], v[92:95], v[36:39]
	v_mfma_f32_16x16x32_bf16 v[24:27], v[168:171], v[80:83], v[24:27]
	v_mfma_f32_16x16x32_bf16 v[20:23], v[176:179], v[80:83], v[20:23]
	v_mfma_f32_16x16x32_bf16 v[8:11], v[168:171], v[72:75], v[8:11]
	v_mfma_f32_16x16x32_bf16 v[4:7], v[176:179], v[72:75], v[2:5]
	s_setprio 0
	s_branch .LBB0_1282
.Lq6_entry:
	v_mov_b32_e32 v4, 0
	v_mov_b32_e32 v5, 0
	v_mov_b32_e32 v6, 0
	v_mov_b32_e32 v7, 0
	v_mov_b32_e32 v8, 0
	v_mov_b32_e32 v9, 0
	v_mov_b32_e32 v10, 0
	v_mov_b32_e32 v11, 0
	v_mov_b32_e32 v12, 0
	v_mov_b32_e32 v13, 0
	v_mov_b32_e32 v14, 0
	v_mov_b32_e32 v15, 0
	v_mov_b32_e32 v16, 0
	v_mov_b32_e32 v17, 0
	v_mov_b32_e32 v18, 0
	v_mov_b32_e32 v19, 0
	v_mov_b32_e32 v20, 0
	v_mov_b32_e32 v21, 0
	v_mov_b32_e32 v22, 0
	v_mov_b32_e32 v23, 0
	v_mov_b32_e32 v24, 0
	v_mov_b32_e32 v25, 0
	v_mov_b32_e32 v26, 0
	v_mov_b32_e32 v27, 0
	v_mov_b32_e32 v28, 0
	v_mov_b32_e32 v29, 0
	v_mov_b32_e32 v30, 0
	v_mov_b32_e32 v31, 0
	v_mov_b32_e32 v32, 0
	v_mov_b32_e32 v33, 0
	v_mov_b32_e32 v34, 0
	v_mov_b32_e32 v35, 0
	v_mov_b32_e32 v36, 0
	v_mov_b32_e32 v37, 0
	v_mov_b32_e32 v38, 0
	v_mov_b32_e32 v39, 0
	v_mov_b32_e32 v40, 0
	v_mov_b32_e32 v41, 0
	v_mov_b32_e32 v42, 0
	v_mov_b32_e32 v43, 0
	v_mov_b32_e32 v44, 0
	v_mov_b32_e32 v45, 0
	v_mov_b32_e32 v46, 0
	v_mov_b32_e32 v47, 0
	v_mov_b32_e32 v48, 0
	v_mov_b32_e32 v49, 0
	v_mov_b32_e32 v50, 0
	v_mov_b32_e32 v51, 0
	v_cmp_ne_u32_e64 s[4:5], 1, v251
	s_andn2_b64 vcc, exec, s[34:35]
	s_add_u32 s40, s38, 0xfff80080
	s_addc_u32 s41, s39, -1
	s_cmp_eq_u32 s84, 28
	s_cselect_b32 s47, s29, s41
	s_cselect_b32 s46, s28, s40
	s_cselect_b32 s41, s37, s27
	s_cselect_b32 s40, s36, s16
	s_mov_b32 m0, s49
	v_lshl_add_u64 v[2:3], s[40:41], 0, v[230:231]
	s_add_u32 s86, s40, 0x80000
	global_load_lds_dwordx4 v[2:3], off
	v_lshl_add_u64 v[236:237], s[40:41], 0, v[228:229]
	s_mov_b32 m0, s50
	s_addc_u32 s87, s41, 0
	global_load_lds_dwordx4 v[236:237], off
	v_lshl_add_u64 v[54:55], s[86:87], 0, v[230:231]
	s_mov_b32 m0, s61
	v_lshl_add_u64 v[238:239], s[46:47], 0, v[230:231]
	v_lshl_add_u64 v[54:55], s[86:87], 0, v[228:229]
	s_mov_b32 m0, s62
	v_lshl_add_u64 v[240:241], s[46:47], 0, v[228:229]
	s_mov_b32 m0, s56
	s_and_b64 vcc, exec, s[4:5]
	global_load_lds_dwordx4 v[238:239], off
	s_mov_b32 m0, s57
	s_nop 0
	global_load_lds_dwordx4 v[240:241], off
	s_and_b64 vcc, exec, s[4:5]
	s_mov_b32 m0, s65
	v_lshl_add_u64 v[2:3], v[2:3], 0, s[14:15]
	s_add_u32 s40, s40, 0x80080
	global_load_lds_dwordx4 v[2:3], off
	v_lshl_add_u64 v[2:3], v[236:237], 0, s[14:15]
	s_mov_b32 m0, s66
	s_addc_u32 s41, s41, 0
	global_load_lds_dwordx4 v[2:3], off
	v_lshl_add_u64 v[2:3], s[40:41], 0, v[230:231]
	s_add_i32 m0, s44, 0x20000
	s_and_b64 vcc, exec, s[4:5]
	v_lshl_add_u64 v[2:3], s[40:41], 0, v[228:229]
	s_add_i32 m0, s44, 0x22000
	s_nop 0
	v_lshl_add_u64 v[2:3], v[238:239], 0, s[14:15]
	s_add_i32 m0, s44, 0xc000
	s_nop 0
	global_load_lds_dwordx4 v[2:3], off
	v_lshl_add_u64 v[2:3], v[240:241], 0, s[14:15]
	s_add_i32 m0, s44, 0xe000
	s_nop 0
	global_load_lds_dwordx4 v[2:3], off
	s_add_u32 s38, s38, 0x100
	s_addc_u32 s39, s39, 0
	s_add_u32 s16, s16, 0x100
	s_addc_u32 s27, s27, 0
	s_branch .Lq6_top
	s_nop 0
	s_nop 0
	s_nop 0
	s_nop 0
	s_nop 0
